# nt hint on the read-once streaming loads of the GLA-side mix build (OF, OB, z_gla)
# speedup vs baseline: 1.0441x; 1.0097x over previous
.LBB0_311:
	s_nop 0
	v_lshl_add_u64 v[10:11], s[34:35], 0, v[52:53]
	v_add_co_u32_e32 v60, vcc, 0x27000000, v10
	v_lshl_add_u64 v[74:75], s[34:35], 0, v[54:55]
	s_nop 0
	v_addc_co_u32_e32 v61, vcc, 0, v11, vcc
	v_add_co_u32_e32 v72, vcc, 0x2b000000, v10
	global_load_dwordx4 v[46:49], v[60:61], off nt
	s_nop 0
	v_addc_co_u32_e32 v73, vcc, 0, v11, vcc
	global_load_dwordx4 v[56:59], v[72:73], off nt
	global_load_dwordx4 v[68:71], v[74:75], off offset:-256 nt
	global_load_dwordx4 v[42:45], v[60:61], off offset:1024 nt
	global_load_dwordx4 v[38:41], v[72:73], off offset:1024 nt
	global_load_dwordx4 v[34:37], v[74:75], off offset:-128 nt
	global_load_dwordx4 v[30:33], v[60:61], off offset:2048 nt
	global_load_dwordx4 v[26:29], v[72:73], off offset:2048 nt
	global_load_dwordx4 v[22:25], v[74:75], off nt
	global_load_dwordx4 v[18:21], v[60:61], off offset:3072 nt
	global_load_dwordx4 v[14:17], v[72:73], off offset:3072 nt
	global_load_dwordx4 v[10:13], v[74:75], off offset:128 nt
	s_add_i32 s4, s4, s6
	v_lshl_add_u64 v[52:53], v[52:53], 0, s[10:11]
	v_lshl_add_u64 v[54:55], v[54:55], 0, s[12:13]
	s_cmp_lt_i32 s4, 0x10000
	s_waitcnt vmcnt(9)
	v_lshlrev_b32_e32 v67, 16, v70
	v_and_b32_e32 v70, 0xffff0000, v70
	v_lshlrev_b32_e32 v60, 16, v49
	v_and_b32_e32 v61, 0xffff0000, v49
	v_lshlrev_b32_e32 v72, 16, v59
	v_and_b32_e32 v73, 0xffff0000, v59
	v_pk_add_f32 v[60:61], v[60:61], v[72:73]
	v_lshlrev_b32_e32 v72, 16, v48
	v_and_b32_e32 v73, 0xffff0000, v48
	v_lshlrev_b32_e32 v48, 16, v58
	v_and_b32_e32 v49, 0xffff0000, v58
	v_pk_add_f32 v[48:49], v[72:73], v[48:49]
	v_mov_b32_e32 v58, v60
	v_mov_b32_e32 v59, v48
	v_pk_mul_f32 v[58:59], v[58:59], v[58:59]
	v_mov_b32_e32 v72, v61
	v_mov_b32_e32 v73, v49
	v_pk_fma_f32 v[58:59], v[72:73], v[72:73], v[58:59]
	v_mul_f32_e32 v72, 0xbfb8aa3b, v67
	v_mul_f32_e32 v73, 0xbfb8aa3b, v70
	v_exp_f32_e32 v72, v72
	v_exp_f32_e32 v73, v73
	s_nop 0
	v_pk_add_f32 v[72:73], v[72:73], 1.0 op_sel_hi:[1,0]
	s_nop 0
	v_div_scale_f32 v74, s[0:1], v73, v73, v70
	v_rcp_f32_e32 v75, v74
	s_nop 0
	v_fma_f32 v76, -v74, v75, 1.0
	v_fmac_f32_e32 v75, v76, v75
	v_div_scale_f32 v76, vcc, v70, v73, v70
	v_mul_f32_e32 v77, v76, v75
	v_fma_f32 v78, -v74, v77, v76
	v_fmac_f32_e32 v77, v78, v75
	v_fma_f32 v74, -v74, v77, v76
	v_div_fmas_f32 v74, v74, v75, v77
	v_div_fixup_f32 v73, v74, v73, v70
	v_div_scale_f32 v70, s[0:1], v72, v72, v67
	v_rcp_f32_e32 v74, v70
	s_nop 0
	v_fma_f32 v75, -v70, v74, 1.0
	v_fmac_f32_e32 v74, v75, v74
	v_div_scale_f32 v75, vcc, v67, v72, v67
	v_mul_f32_e32 v76, v75, v74
	v_fma_f32 v77, -v70, v76, v75
	v_fmac_f32_e32 v76, v77, v74
	v_fma_f32 v70, -v70, v76, v75
	v_div_fmas_f32 v70, v70, v74, v76
	v_lshlrev_b32_e32 v74, 16, v47
	v_and_b32_e32 v75, 0xffff0000, v47
	v_lshlrev_b32_e32 v47, 16, v69
	v_div_fixup_f32 v72, v70, v72, v67
	v_lshlrev_b32_e32 v76, 16, v57
	v_and_b32_e32 v77, 0xffff0000, v57
	v_and_b32_e32 v57, 0xffff0000, v69
	v_mul_f32_e32 v67, 0xbfb8aa3b, v47
	v_pk_add_f32 v[74:75], v[74:75], v[76:77]
	v_exp_f32_e32 v76, v67
	v_mul_f32_e32 v67, 0xbfb8aa3b, v57
	v_exp_f32_e32 v77, v67
	s_nop 0
	v_pk_add_f32 v[76:77], v[76:77], 1.0 op_sel_hi:[1,0]
	s_nop 0
	v_div_scale_f32 v67, s[0:1], v77, v77, v57
	v_rcp_f32_e32 v69, v67
	s_nop 0
	v_fma_f32 v70, -v67, v69, 1.0
	v_fmac_f32_e32 v69, v70, v69
	v_div_scale_f32 v70, vcc, v57, v77, v57
	v_mul_f32_e32 v78, v70, v69
	v_fma_f32 v79, -v67, v78, v70
	v_fmac_f32_e32 v78, v79, v69
	v_fma_f32 v67, -v67, v78, v70
	v_div_fmas_f32 v67, v67, v69, v78
	v_div_fixup_f32 v77, v67, v77, v57
	v_div_scale_f32 v57, s[0:1], v76, v76, v47
	v_rcp_f32_e32 v67, v57
	v_and_b32_e32 v79, 0xffff0000, v46
	v_fma_f32 v69, -v57, v67, 1.0
	v_fmac_f32_e32 v67, v69, v67
	v_div_scale_f32 v69, vcc, v47, v76, v47
	v_mul_f32_e32 v70, v69, v67
	v_fma_f32 v78, -v57, v70, v69
	v_fmac_f32_e32 v70, v78, v67
	v_fma_f32 v57, -v57, v70, v69
	v_div_fmas_f32 v57, v57, v67, v70
	v_div_fixup_f32 v76, v57, v76, v47
	v_lshlrev_b32_e32 v78, 16, v46
	v_lshlrev_b32_e32 v46, 16, v56
	v_and_b32_e32 v47, 0xffff0000, v56
	v_pk_add_f32 v[46:47], v[78:79], v[46:47]
	v_mov_b32_e32 v57, v74
	v_mov_b32_e32 v56, v46
	v_pk_mul_f32 v[56:57], v[56:57], v[56:57]
	v_mov_b32_e32 v78, v47
	v_mov_b32_e32 v79, v75
	v_lshlrev_b32_e32 v67, 16, v68
	v_and_b32_e32 v70, 0xffff0000, v68
	v_pk_fma_f32 v[56:57], v[78:79], v[78:79], v[56:57]
	v_mul_f32_e32 v68, 0xbfb8aa3b, v67
	v_mul_f32_e32 v69, 0xbfb8aa3b, v70
	v_exp_f32_e32 v68, v68
	v_exp_f32_e32 v69, v69
	v_add_f32_e32 v56, v56, v57
	v_add_f32_e32 v56, v59, v56
	v_add_f32_e32 v56, v58, v56
	ds_bpermute_b32 v57, v1, v56
	v_pk_add_f32 v[68:69], v[68:69], 1.0 op_sel_hi:[1,0]
	s_waitcnt lgkmcnt(0)
	v_add_f32_e32 v56, v56, v57
	v_div_scale_f32 v78, s[0:1], v69, v69, v70
	v_rcp_f32_e32 v79, v78
	ds_bpermute_b32 v57, v62, v56
	v_fma_f32 v80, -v78, v79, 1.0
	v_fmac_f32_e32 v79, v80, v79
	v_div_scale_f32 v80, vcc, v70, v69, v70
	v_mul_f32_e32 v81, v80, v79
	v_fma_f32 v82, -v78, v81, v80
	v_fmac_f32_e32 v81, v82, v79
	s_waitcnt lgkmcnt(0)
	v_add_f32_e32 v56, v56, v57
	v_fma_f32 v78, -v78, v81, v80
	ds_bpermute_b32 v57, v63, v56
	v_div_fmas_f32 v78, v78, v79, v81
	v_div_fixup_f32 v69, v78, v69, v70
	v_div_scale_f32 v70, s[0:1], v68, v68, v67
	v_rcp_f32_e32 v78, v70
	s_waitcnt lgkmcnt(0)
	v_add_f32_e32 v56, v56, v57
	ds_bpermute_b32 v57, v64, v56
	v_fma_f32 v79, -v70, v78, 1.0
	v_fmac_f32_e32 v78, v79, v78
	v_div_scale_f32 v79, vcc, v67, v68, v67
	v_mul_f32_e32 v80, v79, v78
	v_fma_f32 v81, -v70, v80, v79
	v_fmac_f32_e32 v80, v81, v78
	s_waitcnt lgkmcnt(0)
	v_add_f32_e32 v56, v56, v57
	v_fma_f32 v70, -v70, v80, v79
	v_fmamk_f32 v56, v56, 0x3c000000, v65
	v_div_fmas_f32 v70, v70, v78, v80
	v_cmp_gt_f32_e32 vcc, s5, v56
	v_mul_f32_e32 v57, 0x4f800000, v56
	v_div_fixup_f32 v68, v70, v68, v67
	v_cndmask_b32_e32 v56, v56, v57, vcc
	v_sqrt_f32_e32 v57, v56
	s_nop 0
	v_add_u32_e32 v58, -1, v57
	v_fma_f32 v59, -v58, v57, v56
	v_cmp_ge_f32_e64 s[0:1], 0, v59
	v_add_u32_e32 v59, 1, v57
	s_nop 0
	v_cndmask_b32_e64 v58, v57, v58, s[0:1]
	v_fma_f32 v57, -v59, v57, v56
	v_cmp_lt_f32_e64 s[0:1], 0, v57
	s_nop 1
	v_cndmask_b32_e64 v57, v58, v59, s[0:1]
	v_mul_f32_e32 v58, 0x37800000, v57
	v_cndmask_b32_e32 v57, v57, v58, vcc
	v_cmp_class_f32_e32 vcc, v56, v66
	s_nop 1
	v_cndmask_b32_e32 v56, v57, v56, vcc
	v_div_scale_f32 v57, s[0:1], v56, v56, 1.0
	v_rcp_f32_e32 v58, v57
	s_nop 0
	v_fma_f32 v59, -v57, v58, 1.0
	v_fmac_f32_e32 v58, v59, v58
	v_div_scale_f32 v59, vcc, 1.0, v56, 1.0
	v_mul_f32_e32 v67, v59, v58
	v_fma_f32 v70, -v57, v67, v59
	v_fmac_f32_e32 v67, v70, v58
	v_fma_f32 v57, -v57, v67, v59
	v_div_fmas_f32 v57, v57, v58, v67
	v_div_fixup_f32 v56, v57, v56, 1.0
	v_pk_mul_f32 v[48:49], v[48:49], v[56:57] op_sel_hi:[1,0]
	v_pk_mul_f32 v[46:47], v[46:47], v[56:57] op_sel_hi:[1,0]
	v_pk_mul_f32 v[58:59], v[74:75], v[56:57] op_sel_hi:[1,0]
	v_pk_mul_f32 v[48:49], v[6:7], v[48:49]
	v_pk_mul_f32 v[46:47], v[2:3], v[46:47]
	v_pk_mul_f32 v[58:59], v[4:5], v[58:59]
	v_pk_mul_f32 v[48:49], v[72:73], v[48:49]
	v_pk_mul_f32 v[46:47], v[68:69], v[46:47]
	v_pk_mul_f32 v[58:59], v[76:77], v[58:59]
	v_cvt_pk_bf16_f32 v48, v48, v49
	v_lshlrev_b32_e32 v49, 16, v71
	v_and_b32_e32 v67, 0xffff0000, v71
	v_cvt_pk_bf16_f32 v46, v46, v47
	v_cvt_pk_bf16_f32 v47, v58, v59
	v_mul_f32_e32 v57, 0xbfb8aa3b, v49
	v_mul_f32_e32 v59, 0xbfb8aa3b, v67
	v_exp_f32_e32 v58, v57
	v_exp_f32_e32 v59, v59
	v_pk_mul_f32 v[56:57], v[60:61], v[56:57] op_sel_hi:[1,0]
	v_pk_add_f32 v[58:59], v[58:59], 1.0 op_sel_hi:[1,0]
	s_nop 0
	v_div_scale_f32 v60, s[0:1], v59, v59, v67
	v_rcp_f32_e32 v61, v60
	v_pk_mul_f32 v[56:57], v[8:9], v[56:57]
	v_fma_f32 v68, -v60, v61, 1.0
	v_fmac_f32_e32 v61, v68, v61
	v_div_scale_f32 v68, vcc, v67, v59, v67
	v_mul_f32_e32 v69, v68, v61
	v_fma_f32 v70, -v60, v69, v68
	v_fmac_f32_e32 v69, v70, v61
	v_fma_f32 v60, -v60, v69, v68
	v_div_fmas_f32 v60, v60, v61, v69
	v_div_fixup_f32 v59, v60, v59, v67
	v_div_scale_f32 v60, s[0:1], v58, v58, v49
	v_rcp_f32_e32 v61, v60
	s_nop 0
	v_fma_f32 v67, -v60, v61, 1.0
	v_fmac_f32_e32 v61, v67, v61
	v_div_scale_f32 v67, vcc, v49, v58, v49
	v_mul_f32_e32 v68, v67, v61
	v_fma_f32 v69, -v60, v68, v67
	v_fmac_f32_e32 v68, v69, v61
	v_fma_f32 v60, -v60, v68, v67
	v_div_fmas_f32 v60, v60, v61, v68
	v_div_fixup_f32 v58, v60, v58, v49
	v_pk_mul_f32 v[56:57], v[58:59], v[56:57]
	s_waitcnt vmcnt(6)
	v_lshlrev_b32_e32 v60, 16, v36
	v_cvt_pk_bf16_f32 v49, v56, v57
	v_lshl_add_u64 v[56:57], s[34:35], 0, v[50:51]
	v_add_co_u32_e32 v58, vcc, s7, v56
	v_and_b32_e32 v36, 0xffff0000, v36
	s_nop 0
	v_addc_co_u32_e32 v59, vcc, 0, v57, vcc
	v_add_co_u32_e32 v56, vcc, s14, v56
	v_lshl_add_u64 v[50:51], v[50:51], 0, s[8:9]
	s_nop 0
	v_addc_co_u32_e32 v57, vcc, 0, v57, vcc
	global_store_dwordx4 v[56:57], v[46:49], off offset:-4096
	s_nop 1
	v_lshlrev_b32_e32 v46, 16, v45
	v_and_b32_e32 v47, 0xffff0000, v45
	v_lshlrev_b32_e32 v48, 16, v41
	v_and_b32_e32 v49, 0xffff0000, v41
	v_pk_add_f32 v[46:47], v[46:47], v[48:49]
	v_lshlrev_b32_e32 v48, 16, v44
	v_and_b32_e32 v49, 0xffff0000, v44
	v_lshlrev_b32_e32 v44, 16, v40
	v_and_b32_e32 v45, 0xffff0000, v40
	v_pk_add_f32 v[40:41], v[48:49], v[44:45]
	v_mov_b32_e32 v44, v46
	v_mov_b32_e32 v45, v40
	v_pk_mul_f32 v[44:45], v[44:45], v[44:45]
	v_mov_b32_e32 v48, v47
	v_mov_b32_e32 v49, v41
	v_pk_fma_f32 v[44:45], v[48:49], v[48:49], v[44:45]
	v_mul_f32_e32 v48, 0xbfb8aa3b, v60
	v_mul_f32_e32 v49, 0xbfb8aa3b, v36
	v_exp_f32_e32 v48, v48
	v_exp_f32_e32 v49, v49
	s_nop 0
	v_pk_add_f32 v[48:49], v[48:49], 1.0 op_sel_hi:[1,0]
	s_nop 0
	v_div_scale_f32 v61, s[0:1], v49, v49, v36
	v_rcp_f32_e32 v67, v61
	s_nop 0
	v_fma_f32 v68, -v61, v67, 1.0
	v_fmac_f32_e32 v67, v68, v67
	v_div_scale_f32 v68, vcc, v36, v49, v36
	v_mul_f32_e32 v69, v68, v67
	v_fma_f32 v70, -v61, v69, v68
	v_fmac_f32_e32 v69, v70, v67
	v_fma_f32 v61, -v61, v69, v68
	v_div_fmas_f32 v61, v61, v67, v69
	v_div_fixup_f32 v49, v61, v49, v36
	v_div_scale_f32 v36, s[0:1], v48, v48, v60
	v_rcp_f32_e32 v61, v36
	s_nop 0
	v_fma_f32 v67, -v36, v61, 1.0
	v_fmac_f32_e32 v61, v67, v61
	v_div_scale_f32 v67, vcc, v60, v48, v60
	v_mul_f32_e32 v68, v67, v61
	v_fma_f32 v69, -v36, v68, v67
	v_fmac_f32_e32 v68, v69, v61
	v_fma_f32 v36, -v36, v68, v67
	v_div_fmas_f32 v36, v36, v61, v68
	v_div_fixup_f32 v48, v36, v48, v60
	v_lshlrev_b32_e32 v36, 16, v35
	v_lshlrev_b32_e32 v60, 16, v43
	v_and_b32_e32 v61, 0xffff0000, v43
	v_lshlrev_b32_e32 v68, 16, v39
	v_and_b32_e32 v69, 0xffff0000, v39
	v_and_b32_e32 v35, 0xffff0000, v35
	v_mul_f32_e32 v39, 0xbfb8aa3b, v36
	v_pk_add_f32 v[60:61], v[60:61], v[68:69]
	v_exp_f32_e32 v68, v39
	v_mul_f32_e32 v39, 0xbfb8aa3b, v35
	v_exp_f32_e32 v69, v39
	s_nop 0
	v_pk_add_f32 v[68:69], v[68:69], 1.0 op_sel_hi:[1,0]
	s_nop 0
	v_div_scale_f32 v39, s[0:1], v69, v69, v35
	v_rcp_f32_e32 v43, v39
	s_nop 0
	v_fma_f32 v67, -v39, v43, 1.0
	v_fmac_f32_e32 v43, v67, v43
	v_div_scale_f32 v67, vcc, v35, v69, v35
	v_mul_f32_e32 v70, v67, v43
	v_fma_f32 v71, -v39, v70, v67
	v_fmac_f32_e32 v70, v71, v43
	v_fma_f32 v39, -v39, v70, v67
	v_div_fmas_f32 v39, v39, v43, v70
	v_div_fixup_f32 v69, v39, v69, v35
	v_div_scale_f32 v35, s[0:1], v68, v68, v36
	v_rcp_f32_e32 v39, v35
	v_and_b32_e32 v71, 0xffff0000, v42
	v_fma_f32 v43, -v35, v39, 1.0
	v_fmac_f32_e32 v39, v43, v39
	v_div_scale_f32 v43, vcc, v36, v68, v36
	v_mul_f32_e32 v67, v43, v39
	v_fma_f32 v70, -v35, v67, v43
	v_fmac_f32_e32 v67, v70, v39
	v_fma_f32 v35, -v35, v67, v43
	v_div_fmas_f32 v35, v35, v39, v67
	v_div_fixup_f32 v68, v35, v68, v36
	v_lshlrev_b32_e32 v36, 16, v34
	v_and_b32_e32 v67, 0xffff0000, v34
	v_mul_f32_e32 v34, 0xbfb8aa3b, v36
	v_mul_f32_e32 v35, 0xbfb8aa3b, v67
	v_exp_f32_e32 v34, v34
	v_exp_f32_e32 v35, v35
	v_lshlrev_b32_e32 v70, 16, v42
	v_lshlrev_b32_e32 v42, 16, v38
	v_and_b32_e32 v43, 0xffff0000, v38
	v_pk_add_f32 v[42:43], v[70:71], v[42:43]
	v_mov_b32_e32 v39, v60
	v_mov_b32_e32 v38, v42
	v_pk_mul_f32 v[38:39], v[38:39], v[38:39]
	v_mov_b32_e32 v70, v43
	v_mov_b32_e32 v71, v61
	v_pk_add_f32 v[34:35], v[34:35], 1.0 op_sel_hi:[1,0]
	v_pk_fma_f32 v[38:39], v[70:71], v[70:71], v[38:39]
	v_div_scale_f32 v70, s[0:1], v35, v35, v67
	v_rcp_f32_e32 v71, v70
	s_nop 0
	v_fma_f32 v72, -v70, v71, 1.0
	v_fmac_f32_e32 v71, v72, v71
	v_div_scale_f32 v72, vcc, v67, v35, v67
	v_mul_f32_e32 v73, v72, v71
	v_fma_f32 v74, -v70, v73, v72
	v_fmac_f32_e32 v73, v74, v71
	v_fma_f32 v70, -v70, v73, v72
	v_div_fmas_f32 v70, v70, v71, v73
	v_div_fixup_f32 v35, v70, v35, v67
	v_div_scale_f32 v67, s[0:1], v34, v34, v36
	v_rcp_f32_e32 v70, v67
	s_nop 0
	v_fma_f32 v71, -v67, v70, 1.0
	v_fmac_f32_e32 v70, v71, v70
	v_div_scale_f32 v71, vcc, v36, v34, v36
	v_mul_f32_e32 v72, v71, v70
	v_fma_f32 v73, -v67, v72, v71
	v_fmac_f32_e32 v72, v73, v70
	v_fma_f32 v67, -v67, v72, v71
	v_div_fmas_f32 v67, v67, v70, v72
	v_div_fixup_f32 v34, v67, v34, v36
	v_add_f32_e32 v36, v38, v39
	v_add_f32_e32 v36, v45, v36
	v_add_f32_e32 v36, v44, v36
	ds_bpermute_b32 v38, v1, v36
	s_waitcnt lgkmcnt(0)
	v_add_f32_e32 v36, v36, v38
	ds_bpermute_b32 v38, v62, v36
	s_waitcnt lgkmcnt(0)
	v_add_f32_e32 v36, v36, v38
	ds_bpermute_b32 v38, v63, v36
	s_waitcnt lgkmcnt(0)
	v_add_f32_e32 v36, v36, v38
	ds_bpermute_b32 v38, v64, v36
	s_waitcnt lgkmcnt(0)
	v_add_f32_e32 v36, v36, v38
	v_fmamk_f32 v36, v36, 0x3c000000, v65
	v_cmp_gt_f32_e32 vcc, s5, v36
	v_mul_f32_e32 v38, 0x4f800000, v36
	s_nop 0
	v_cndmask_b32_e32 v36, v36, v38, vcc
	v_sqrt_f32_e32 v38, v36
	s_nop 0
	v_add_u32_e32 v39, -1, v38
	v_fma_f32 v44, -v39, v38, v36
	v_cmp_ge_f32_e64 s[0:1], 0, v44
	v_add_u32_e32 v44, 1, v38
	s_nop 0
	v_cndmask_b32_e64 v39, v38, v39, s[0:1]
	v_fma_f32 v38, -v44, v38, v36
	v_cmp_lt_f32_e64 s[0:1], 0, v38
	s_nop 1
	v_cndmask_b32_e64 v38, v39, v44, s[0:1]
	v_mul_f32_e32 v39, 0x37800000, v38
	v_cndmask_b32_e32 v38, v38, v39, vcc
	v_cmp_class_f32_e32 vcc, v36, v66
	s_nop 1
	v_cndmask_b32_e32 v36, v38, v36, vcc
	v_div_scale_f32 v38, s[0:1], v36, v36, 1.0
	v_rcp_f32_e32 v39, v38
	s_nop 0
	v_fma_f32 v44, -v38, v39, 1.0
	v_fmac_f32_e32 v39, v44, v39
	v_div_scale_f32 v44, vcc, 1.0, v36, 1.0
	v_mul_f32_e32 v45, v44, v39
	v_fma_f32 v67, -v38, v45, v44
	v_fmac_f32_e32 v45, v67, v39
	v_fma_f32 v38, -v38, v45, v44
	v_div_fmas_f32 v38, v38, v39, v45
	v_div_fixup_f32 v38, v38, v36, 1.0
	v_pk_mul_f32 v[42:43], v[42:43], v[38:39] op_sel_hi:[1,0]
	v_pk_mul_f32 v[40:41], v[40:41], v[38:39] op_sel_hi:[1,0]
	v_pk_mul_f32 v[42:43], v[2:3], v[42:43]
	v_pk_mul_f32 v[40:41], v[6:7], v[40:41]
	v_pk_mul_f32 v[34:35], v[34:35], v[42:43]
	v_pk_mul_f32 v[42:43], v[60:61], v[38:39] op_sel_hi:[1,0]
	v_cvt_pk_bf16_f32 v34, v34, v35
	v_pk_mul_f32 v[42:43], v[4:5], v[42:43]
	v_pk_mul_f32 v[40:41], v[48:49], v[40:41]
	v_pk_mul_f32 v[42:43], v[68:69], v[42:43]
	v_cvt_pk_bf16_f32 v36, v40, v41
	v_cvt_pk_bf16_f32 v35, v42, v43
	v_lshlrev_b32_e32 v42, 16, v37
	v_and_b32_e32 v37, 0xffff0000, v37
	v_mul_f32_e32 v39, 0xbfb8aa3b, v42
	v_mul_f32_e32 v41, 0xbfb8aa3b, v37
	v_exp_f32_e32 v40, v39
	v_exp_f32_e32 v41, v41
	v_pk_mul_f32 v[38:39], v[46:47], v[38:39] op_sel_hi:[1,0]
	v_pk_add_f32 v[40:41], v[40:41], 1.0 op_sel_hi:[1,0]
	s_nop 0
	v_div_scale_f32 v43, s[0:1], v41, v41, v37
	v_rcp_f32_e32 v44, v43
	v_pk_mul_f32 v[38:39], v[8:9], v[38:39]
	v_fma_f32 v45, -v43, v44, 1.0
	v_fmac_f32_e32 v44, v45, v44
	v_div_scale_f32 v45, vcc, v37, v41, v37
	v_mul_f32_e32 v46, v45, v44
	v_fma_f32 v47, -v43, v46, v45
	v_fmac_f32_e32 v46, v47, v44
	v_fma_f32 v43, -v43, v46, v45
	v_div_fmas_f32 v43, v43, v44, v46
	v_div_fixup_f32 v41, v43, v41, v37
	v_div_scale_f32 v37, s[0:1], v40, v40, v42
	v_rcp_f32_e32 v43, v37
	s_nop 0
	v_fma_f32 v44, -v37, v43, 1.0
	v_fmac_f32_e32 v43, v44, v43
	v_div_scale_f32 v44, vcc, v42, v40, v42
	v_mul_f32_e32 v45, v44, v43
	v_fma_f32 v46, -v37, v45, v44
	v_fmac_f32_e32 v45, v46, v43
	v_fma_f32 v37, -v37, v45, v44
	v_div_fmas_f32 v37, v37, v43, v45
	v_div_fixup_f32 v40, v37, v40, v42
	v_pk_mul_f32 v[38:39], v[40:41], v[38:39]
	s_nop 0
	v_cvt_pk_bf16_f32 v37, v38, v39
	global_store_dwordx4 v[58:59], v[34:37], off offset:2048
	s_waitcnt vmcnt(5)
	v_lshlrev_b32_e32 v38, 16, v24
	v_and_b32_e32 v24, 0xffff0000, v24
	v_lshlrev_b32_e32 v34, 16, v33
	v_and_b32_e32 v35, 0xffff0000, v33
	v_lshlrev_b32_e32 v36, 16, v29
	v_and_b32_e32 v37, 0xffff0000, v29
	v_pk_add_f32 v[34:35], v[34:35], v[36:37]
	v_lshlrev_b32_e32 v36, 16, v32
	v_and_b32_e32 v37, 0xffff0000, v32
	v_lshlrev_b32_e32 v32, 16, v28
	v_and_b32_e32 v33, 0xffff0000, v28
	v_pk_add_f32 v[28:29], v[36:37], v[32:33]
	v_mov_b32_e32 v32, v34
	v_mov_b32_e32 v33, v28
	v_pk_mul_f32 v[32:33], v[32:33], v[32:33]
	v_mov_b32_e32 v36, v35
	v_mov_b32_e32 v37, v29
	v_pk_fma_f32 v[32:33], v[36:37], v[36:37], v[32:33]
	v_mul_f32_e32 v36, 0xbfb8aa3b, v38
	v_mul_f32_e32 v37, 0xbfb8aa3b, v24
	v_exp_f32_e32 v36, v36
	v_exp_f32_e32 v37, v37
	s_nop 0
	v_pk_add_f32 v[36:37], v[36:37], 1.0 op_sel_hi:[1,0]
	s_nop 0
	v_div_scale_f32 v39, s[0:1], v37, v37, v24
	v_rcp_f32_e32 v40, v39
	s_nop 0
	v_fma_f32 v41, -v39, v40, 1.0
	v_fmac_f32_e32 v40, v41, v40
	v_div_scale_f32 v41, vcc, v24, v37, v24
	v_mul_f32_e32 v42, v41, v40
	v_fma_f32 v43, -v39, v42, v41
	v_fmac_f32_e32 v42, v43, v40
	v_fma_f32 v39, -v39, v42, v41
	v_div_fmas_f32 v39, v39, v40, v42
	v_div_fixup_f32 v37, v39, v37, v24
	v_div_scale_f32 v24, s[0:1], v36, v36, v38
	v_rcp_f32_e32 v39, v24
	s_nop 0
	v_fma_f32 v40, -v24, v39, 1.0
	v_fmac_f32_e32 v39, v40, v39
	v_div_scale_f32 v40, vcc, v38, v36, v38
	v_mul_f32_e32 v41, v40, v39
	v_fma_f32 v42, -v24, v41, v40
	v_fmac_f32_e32 v41, v42, v39
	v_fma_f32 v24, -v24, v41, v40
	v_div_fmas_f32 v24, v24, v39, v41
	v_div_fixup_f32 v36, v24, v36, v38
	v_lshlrev_b32_e32 v24, 16, v23
	v_lshlrev_b32_e32 v38, 16, v31
	v_and_b32_e32 v39, 0xffff0000, v31
	v_lshlrev_b32_e32 v40, 16, v27
	v_and_b32_e32 v41, 0xffff0000, v27
	v_and_b32_e32 v23, 0xffff0000, v23
	v_mul_f32_e32 v27, 0xbfb8aa3b, v24
	v_pk_add_f32 v[38:39], v[38:39], v[40:41]
	v_exp_f32_e32 v40, v27
	v_mul_f32_e32 v27, 0xbfb8aa3b, v23
	v_exp_f32_e32 v41, v27
	s_nop 0
	v_pk_add_f32 v[40:41], v[40:41], 1.0 op_sel_hi:[1,0]
	s_nop 0
	v_div_scale_f32 v27, s[0:1], v41, v41, v23
	v_rcp_f32_e32 v31, v27
	s_nop 0
	v_fma_f32 v42, -v27, v31, 1.0
	v_fmac_f32_e32 v31, v42, v31
	v_div_scale_f32 v42, vcc, v23, v41, v23
	v_mul_f32_e32 v43, v42, v31
	v_fma_f32 v44, -v27, v43, v42
	v_fmac_f32_e32 v43, v44, v31
	v_fma_f32 v27, -v27, v43, v42
	v_div_fmas_f32 v27, v27, v31, v43
	v_div_fixup_f32 v41, v27, v41, v23
	v_div_scale_f32 v23, s[0:1], v40, v40, v24
	v_rcp_f32_e32 v27, v23
	s_nop 0
	v_fma_f32 v31, -v23, v27, 1.0
	v_fmac_f32_e32 v27, v31, v27
	v_div_scale_f32 v31, vcc, v24, v40, v24
	v_mul_f32_e32 v42, v31, v27
	v_fma_f32 v43, -v23, v42, v31
	v_fmac_f32_e32 v42, v43, v27
	v_fma_f32 v23, -v23, v42, v31
	v_div_fmas_f32 v23, v23, v27, v42
	v_lshlrev_b32_e32 v42, 16, v30
	v_and_b32_e32 v43, 0xffff0000, v30
	v_lshlrev_b32_e32 v30, 16, v26
	v_and_b32_e32 v31, 0xffff0000, v26
	v_pk_add_f32 v[30:31], v[42:43], v[30:31]
	v_mov_b32_e32 v27, v38
	v_mov_b32_e32 v26, v30
	v_pk_mul_f32 v[26:27], v[26:27], v[26:27]
	v_mov_b32_e32 v42, v31
	v_mov_b32_e32 v43, v39
	v_div_fixup_f32 v40, v23, v40, v24
	v_pk_fma_f32 v[26:27], v[42:43], v[42:43], v[26:27]
	v_lshlrev_b32_e32 v24, 16, v22
	v_and_b32_e32 v42, 0xffff0000, v22
	v_mul_f32_e32 v22, 0xbfb8aa3b, v24
	v_mul_f32_e32 v23, 0xbfb8aa3b, v42
	v_exp_f32_e32 v22, v22
	v_exp_f32_e32 v23, v23
	s_nop 0
	v_pk_add_f32 v[22:23], v[22:23], 1.0 op_sel_hi:[1,0]
	s_nop 0
	v_div_scale_f32 v43, s[0:1], v23, v23, v42
	v_rcp_f32_e32 v44, v43
	s_nop 0
	v_fma_f32 v45, -v43, v44, 1.0
	v_fmac_f32_e32 v44, v45, v44
	v_div_scale_f32 v45, vcc, v42, v23, v42
	v_mul_f32_e32 v46, v45, v44
	v_fma_f32 v47, -v43, v46, v45
	v_fmac_f32_e32 v46, v47, v44
	v_fma_f32 v43, -v43, v46, v45
	v_div_fmas_f32 v43, v43, v44, v46
	v_div_fixup_f32 v23, v43, v23, v42
	v_div_scale_f32 v42, s[0:1], v22, v22, v24
	v_rcp_f32_e32 v43, v42
	s_nop 0
	v_fma_f32 v44, -v42, v43, 1.0
	v_fmac_f32_e32 v43, v44, v43
	v_div_scale_f32 v44, vcc, v24, v22, v24
	v_mul_f32_e32 v45, v44, v43
	v_fma_f32 v46, -v42, v45, v44
	v_fmac_f32_e32 v45, v46, v43
	v_fma_f32 v42, -v42, v45, v44
	v_div_fmas_f32 v42, v42, v43, v45
	v_div_fixup_f32 v22, v42, v22, v24
	v_add_f32_e32 v24, v26, v27
	v_add_f32_e32 v24, v33, v24
	v_add_f32_e32 v24, v32, v24
	ds_bpermute_b32 v26, v1, v24
	s_waitcnt lgkmcnt(0)
	v_add_f32_e32 v24, v24, v26
	ds_bpermute_b32 v26, v62, v24
	s_waitcnt lgkmcnt(0)
	v_add_f32_e32 v24, v24, v26
	ds_bpermute_b32 v26, v63, v24
	s_waitcnt lgkmcnt(0)
	v_add_f32_e32 v24, v24, v26
	ds_bpermute_b32 v26, v64, v24
	s_waitcnt lgkmcnt(0)
	v_add_f32_e32 v24, v24, v26
	v_fmamk_f32 v24, v24, 0x3c000000, v65
	v_cmp_gt_f32_e32 vcc, s5, v24
	v_mul_f32_e32 v26, 0x4f800000, v24
	s_nop 0
	v_cndmask_b32_e32 v24, v24, v26, vcc
	v_sqrt_f32_e32 v26, v24
	s_nop 0
	v_add_u32_e32 v27, -1, v26
	v_fma_f32 v32, -v27, v26, v24
	v_cmp_ge_f32_e64 s[0:1], 0, v32
	v_add_u32_e32 v32, 1, v26
	s_nop 0
	v_cndmask_b32_e64 v27, v26, v27, s[0:1]
	v_fma_f32 v26, -v32, v26, v24
	v_cmp_lt_f32_e64 s[0:1], 0, v26
	s_nop 1
	v_cndmask_b32_e64 v26, v27, v32, s[0:1]
	v_mul_f32_e32 v27, 0x37800000, v26
	v_cndmask_b32_e32 v26, v26, v27, vcc
	v_cmp_class_f32_e32 vcc, v24, v66
	s_nop 1
	v_cndmask_b32_e32 v24, v26, v24, vcc
	v_div_scale_f32 v26, s[0:1], v24, v24, 1.0
	v_rcp_f32_e32 v27, v26
	s_nop 0
	v_fma_f32 v32, -v26, v27, 1.0
	v_fmac_f32_e32 v27, v32, v27
	v_div_scale_f32 v32, vcc, 1.0, v24, 1.0
	v_mul_f32_e32 v33, v32, v27
	v_fma_f32 v42, -v26, v33, v32
	v_fmac_f32_e32 v33, v42, v27
	v_fma_f32 v26, -v26, v33, v32
	v_div_fmas_f32 v26, v26, v27, v33
	v_div_fixup_f32 v26, v26, v24, 1.0
	v_pk_mul_f32 v[30:31], v[30:31], v[26:27] op_sel_hi:[1,0]
	v_pk_mul_f32 v[28:29], v[28:29], v[26:27] op_sel_hi:[1,0]
	v_pk_mul_f32 v[30:31], v[2:3], v[30:31]
	v_pk_mul_f32 v[28:29], v[6:7], v[28:29]
	v_pk_mul_f32 v[22:23], v[22:23], v[30:31]
	v_pk_mul_f32 v[30:31], v[38:39], v[26:27] op_sel_hi:[1,0]
	v_cvt_pk_bf16_f32 v22, v22, v23
	v_pk_mul_f32 v[30:31], v[4:5], v[30:31]
	v_pk_mul_f32 v[28:29], v[36:37], v[28:29]
	v_pk_mul_f32 v[30:31], v[40:41], v[30:31]
	v_cvt_pk_bf16_f32 v24, v28, v29
	v_cvt_pk_bf16_f32 v23, v30, v31
	v_lshlrev_b32_e32 v30, 16, v25
	v_and_b32_e32 v25, 0xffff0000, v25
	v_mul_f32_e32 v27, 0xbfb8aa3b, v30
	v_mul_f32_e32 v29, 0xbfb8aa3b, v25
	v_exp_f32_e32 v28, v27
	v_exp_f32_e32 v29, v29
	v_pk_mul_f32 v[26:27], v[34:35], v[26:27] op_sel_hi:[1,0]
	v_pk_add_f32 v[28:29], v[28:29], 1.0 op_sel_hi:[1,0]
	s_nop 0
	v_div_scale_f32 v31, s[0:1], v29, v29, v25
	v_rcp_f32_e32 v32, v31
	v_pk_mul_f32 v[26:27], v[8:9], v[26:27]
	v_fma_f32 v33, -v31, v32, 1.0
	v_fmac_f32_e32 v32, v33, v32
	v_div_scale_f32 v33, vcc, v25, v29, v25
	v_mul_f32_e32 v34, v33, v32
	v_fma_f32 v35, -v31, v34, v33
	v_fmac_f32_e32 v34, v35, v32
	v_fma_f32 v31, -v31, v34, v33
	v_div_fmas_f32 v31, v31, v32, v34
	v_div_fixup_f32 v29, v31, v29, v25
	v_div_scale_f32 v25, s[0:1], v28, v28, v30
	v_rcp_f32_e32 v31, v25
	s_nop 0
	v_fma_f32 v32, -v25, v31, 1.0
	v_fmac_f32_e32 v31, v32, v31
	v_div_scale_f32 v32, vcc, v30, v28, v30
	v_mul_f32_e32 v33, v32, v31
	v_fma_f32 v34, -v25, v33, v32
	v_fmac_f32_e32 v33, v34, v31
	v_fma_f32 v25, -v25, v33, v32
	v_div_fmas_f32 v25, v25, v31, v33
	v_div_fixup_f32 v28, v25, v28, v30
	v_pk_mul_f32 v[26:27], v[28:29], v[26:27]
	s_nop 0
	v_cvt_pk_bf16_f32 v25, v26, v27
	global_store_dwordx4 v[56:57], v[22:25], off
	s_waitcnt vmcnt(3)
	v_lshlrev_b32_e32 v26, 16, v12
	v_and_b32_e32 v12, 0xffff0000, v12
	v_lshlrev_b32_e32 v22, 16, v21
	v_and_b32_e32 v23, 0xffff0000, v21
	v_lshlrev_b32_e32 v24, 16, v17
	v_and_b32_e32 v25, 0xffff0000, v17
	v_pk_add_f32 v[22:23], v[22:23], v[24:25]
	v_lshlrev_b32_e32 v24, 16, v20
	v_and_b32_e32 v25, 0xffff0000, v20
	v_lshlrev_b32_e32 v20, 16, v16
	v_and_b32_e32 v21, 0xffff0000, v16
	v_pk_add_f32 v[16:17], v[24:25], v[20:21]
	v_mov_b32_e32 v20, v22
	v_mov_b32_e32 v21, v16
	v_pk_mul_f32 v[20:21], v[20:21], v[20:21]
	v_mov_b32_e32 v24, v23
	v_mov_b32_e32 v25, v17
	v_pk_fma_f32 v[20:21], v[24:25], v[24:25], v[20:21]
	v_mul_f32_e32 v24, 0xbfb8aa3b, v26
	v_mul_f32_e32 v25, 0xbfb8aa3b, v12
	v_exp_f32_e32 v24, v24
	v_exp_f32_e32 v25, v25
	s_nop 0
	v_pk_add_f32 v[24:25], v[24:25], 1.0 op_sel_hi:[1,0]
	s_nop 0
	v_div_scale_f32 v27, s[0:1], v25, v25, v12
	v_rcp_f32_e32 v28, v27
	s_nop 0
	v_fma_f32 v29, -v27, v28, 1.0
	v_fmac_f32_e32 v28, v29, v28
	v_div_scale_f32 v29, vcc, v12, v25, v12
	v_mul_f32_e32 v30, v29, v28
	v_fma_f32 v31, -v27, v30, v29
	v_fmac_f32_e32 v30, v31, v28
	v_fma_f32 v27, -v27, v30, v29
	v_div_fmas_f32 v27, v27, v28, v30
	v_div_fixup_f32 v25, v27, v25, v12
	v_div_scale_f32 v12, s[0:1], v24, v24, v26
	v_rcp_f32_e32 v27, v12
	s_nop 0
	v_fma_f32 v28, -v12, v27, 1.0
	v_fmac_f32_e32 v27, v28, v27
	v_div_scale_f32 v28, vcc, v26, v24, v26
	v_mul_f32_e32 v29, v28, v27
	v_fma_f32 v30, -v12, v29, v28
	v_fmac_f32_e32 v29, v30, v27
	v_fma_f32 v12, -v12, v29, v28
	v_div_fmas_f32 v12, v12, v27, v29
	v_div_fixup_f32 v24, v12, v24, v26
	v_lshlrev_b32_e32 v12, 16, v11
	v_lshlrev_b32_e32 v26, 16, v19
	v_and_b32_e32 v27, 0xffff0000, v19
	v_lshlrev_b32_e32 v28, 16, v15
	v_and_b32_e32 v29, 0xffff0000, v15
	v_and_b32_e32 v11, 0xffff0000, v11
	v_mul_f32_e32 v15, 0xbfb8aa3b, v12
	v_pk_add_f32 v[26:27], v[26:27], v[28:29]
	v_exp_f32_e32 v28, v15
	v_mul_f32_e32 v15, 0xbfb8aa3b, v11
	v_exp_f32_e32 v29, v15
	s_nop 0
	v_pk_add_f32 v[28:29], v[28:29], 1.0 op_sel_hi:[1,0]
	s_nop 0
	v_div_scale_f32 v15, s[0:1], v29, v29, v11
	v_rcp_f32_e32 v19, v15
	s_nop 0
	v_fma_f32 v30, -v15, v19, 1.0
	v_fmac_f32_e32 v19, v30, v19
	v_div_scale_f32 v30, vcc, v11, v29, v11
	v_mul_f32_e32 v31, v30, v19
	v_fma_f32 v32, -v15, v31, v30
	v_fmac_f32_e32 v31, v32, v19
	v_fma_f32 v15, -v15, v31, v30
	v_div_fmas_f32 v15, v15, v19, v31
	v_div_fixup_f32 v29, v15, v29, v11
	v_div_scale_f32 v11, s[0:1], v28, v28, v12
	v_rcp_f32_e32 v15, v11
	s_nop 0
	v_fma_f32 v19, -v11, v15, 1.0
	v_fmac_f32_e32 v15, v19, v15
	v_div_scale_f32 v19, vcc, v12, v28, v12
	v_mul_f32_e32 v30, v19, v15
	v_fma_f32 v31, -v11, v30, v19
	v_fmac_f32_e32 v30, v31, v15
	v_fma_f32 v11, -v11, v30, v19
	v_div_fmas_f32 v11, v11, v15, v30
	v_lshlrev_b32_e32 v30, 16, v18
	v_and_b32_e32 v31, 0xffff0000, v18
	v_lshlrev_b32_e32 v18, 16, v14
	v_and_b32_e32 v19, 0xffff0000, v14
	v_pk_add_f32 v[18:19], v[30:31], v[18:19]
	v_mov_b32_e32 v15, v26
	v_mov_b32_e32 v14, v18
	v_pk_mul_f32 v[14:15], v[14:15], v[14:15]
	v_mov_b32_e32 v30, v19
	v_mov_b32_e32 v31, v27
	v_div_fixup_f32 v28, v11, v28, v12
	v_pk_fma_f32 v[14:15], v[30:31], v[30:31], v[14:15]
	v_lshlrev_b32_e32 v12, 16, v10
	v_and_b32_e32 v30, 0xffff0000, v10
	v_mul_f32_e32 v10, 0xbfb8aa3b, v12
	v_mul_f32_e32 v11, 0xbfb8aa3b, v30
	v_exp_f32_e32 v10, v10
	v_exp_f32_e32 v11, v11
	s_nop 0
	v_pk_add_f32 v[10:11], v[10:11], 1.0 op_sel_hi:[1,0]
	s_nop 0
	v_div_scale_f32 v31, s[0:1], v11, v11, v30
	v_rcp_f32_e32 v32, v31
	s_nop 0
	v_fma_f32 v33, -v31, v32, 1.0
	v_fmac_f32_e32 v32, v33, v32
	v_div_scale_f32 v33, vcc, v30, v11, v30
	v_mul_f32_e32 v34, v33, v32
	v_fma_f32 v35, -v31, v34, v33
	v_fmac_f32_e32 v34, v35, v32
	v_fma_f32 v31, -v31, v34, v33
	v_div_fmas_f32 v31, v31, v32, v34
	v_div_fixup_f32 v11, v31, v11, v30
	v_div_scale_f32 v30, s[0:1], v10, v10, v12
	v_rcp_f32_e32 v31, v30
	s_nop 0
	v_fma_f32 v32, -v30, v31, 1.0
	v_fmac_f32_e32 v31, v32, v31
	v_div_scale_f32 v32, vcc, v12, v10, v12
	v_mul_f32_e32 v33, v32, v31
	v_fma_f32 v34, -v30, v33, v32
	v_fmac_f32_e32 v33, v34, v31
	v_fma_f32 v30, -v30, v33, v32
	v_div_fmas_f32 v30, v30, v31, v33
	v_div_fixup_f32 v10, v30, v10, v12
	v_add_f32_e32 v12, v14, v15
	v_add_f32_e32 v12, v21, v12
	v_add_f32_e32 v12, v20, v12
	ds_bpermute_b32 v14, v1, v12
	s_waitcnt lgkmcnt(0)
	v_add_f32_e32 v12, v12, v14
	ds_bpermute_b32 v14, v62, v12
	s_waitcnt lgkmcnt(0)
	v_add_f32_e32 v12, v12, v14
	ds_bpermute_b32 v14, v63, v12
	s_waitcnt lgkmcnt(0)
	v_add_f32_e32 v12, v12, v14
	ds_bpermute_b32 v14, v64, v12
	s_waitcnt lgkmcnt(0)
	v_add_f32_e32 v12, v12, v14
	v_fmamk_f32 v12, v12, 0x3c000000, v65
	v_cmp_gt_f32_e32 vcc, s5, v12
	v_mul_f32_e32 v14, 0x4f800000, v12
	s_nop 0
	v_cndmask_b32_e32 v12, v12, v14, vcc
	v_sqrt_f32_e32 v14, v12
	s_nop 0
	v_add_u32_e32 v15, -1, v14
	v_fma_f32 v20, -v15, v14, v12
	v_cmp_ge_f32_e64 s[0:1], 0, v20
	v_add_u32_e32 v20, 1, v14
	s_nop 0
	v_cndmask_b32_e64 v15, v14, v15, s[0:1]
	v_fma_f32 v14, -v20, v14, v12
	v_cmp_lt_f32_e64 s[0:1], 0, v14
	s_nop 1
	v_cndmask_b32_e64 v14, v15, v20, s[0:1]
	v_mul_f32_e32 v15, 0x37800000, v14
	v_cndmask_b32_e32 v14, v14, v15, vcc
	v_cmp_class_f32_e32 vcc, v12, v66
	s_nop 1
	v_cndmask_b32_e32 v12, v14, v12, vcc
	v_div_scale_f32 v14, s[0:1], v12, v12, 1.0
	v_rcp_f32_e32 v15, v14
	s_nop 0
	v_fma_f32 v20, -v14, v15, 1.0
	v_fmac_f32_e32 v15, v20, v15
	v_div_scale_f32 v20, vcc, 1.0, v12, 1.0
	v_mul_f32_e32 v21, v20, v15
	v_fma_f32 v30, -v14, v21, v20
	v_fmac_f32_e32 v21, v30, v15
	v_fma_f32 v14, -v14, v21, v20
	v_div_fmas_f32 v14, v14, v15, v21
	v_div_fixup_f32 v14, v14, v12, 1.0
	v_pk_mul_f32 v[18:19], v[18:19], v[14:15] op_sel_hi:[1,0]
	v_pk_mul_f32 v[16:17], v[16:17], v[14:15] op_sel_hi:[1,0]
	v_pk_mul_f32 v[18:19], v[2:3], v[18:19]
	v_pk_mul_f32 v[16:17], v[6:7], v[16:17]
	v_pk_mul_f32 v[10:11], v[10:11], v[18:19]
	v_pk_mul_f32 v[18:19], v[26:27], v[14:15] op_sel_hi:[1,0]
	v_cvt_pk_bf16_f32 v10, v10, v11
	v_pk_mul_f32 v[18:19], v[4:5], v[18:19]
	v_pk_mul_f32 v[16:17], v[24:25], v[16:17]
	v_pk_mul_f32 v[18:19], v[28:29], v[18:19]
	v_cvt_pk_bf16_f32 v12, v16, v17
	v_cvt_pk_bf16_f32 v11, v18, v19
	v_lshlrev_b32_e32 v18, 16, v13
	v_and_b32_e32 v13, 0xffff0000, v13
	v_mul_f32_e32 v15, 0xbfb8aa3b, v18
	v_mul_f32_e32 v17, 0xbfb8aa3b, v13
	v_exp_f32_e32 v16, v15
	v_exp_f32_e32 v17, v17
	v_pk_mul_f32 v[14:15], v[22:23], v[14:15] op_sel_hi:[1,0]
	v_pk_add_f32 v[16:17], v[16:17], 1.0 op_sel_hi:[1,0]
	s_nop 0
	v_div_scale_f32 v19, s[0:1], v17, v17, v13
	v_rcp_f32_e32 v20, v19
	v_pk_mul_f32 v[14:15], v[8:9], v[14:15]
	v_fma_f32 v21, -v19, v20, 1.0
	v_fmac_f32_e32 v20, v21, v20
	v_div_scale_f32 v21, vcc, v13, v17, v13
	v_mul_f32_e32 v22, v21, v20
	v_fma_f32 v23, -v19, v22, v21
	v_fmac_f32_e32 v22, v23, v20
	v_fma_f32 v19, -v19, v22, v21
	v_div_fmas_f32 v19, v19, v20, v22
	v_div_fixup_f32 v17, v19, v17, v13
	v_div_scale_f32 v19, s[0:1], v16, v16, v18
	v_rcp_f32_e32 v13, v19
	s_nop 0
	v_fma_f32 v20, -v19, v13, 1.0
	v_fmac_f32_e32 v13, v20, v13
	v_div_scale_f32 v20, vcc, v18, v16, v18
	v_mul_f32_e32 v21, v20, v13
	v_fma_f32 v22, -v19, v21, v20
	v_fmac_f32_e32 v21, v22, v13
	v_fma_f32 v19, -v19, v21, v20
	v_div_fmas_f32 v13, v19, v13, v21
	v_div_fixup_f32 v16, v13, v16, v18
	v_pk_mul_f32 v[14:15], v[16:17], v[14:15]
	s_nop 0
	v_cvt_pk_bf16_f32 v13, v14, v15
	global_store_dwordx4 v[56:57], v[10:13], off offset:2048
	s_cbranch_scc1 .LBB0_311
